# gmlp prompt W/V staging loops unrolled with all loads in flight; ph0 loop register rotation moved after next-tile decode
# speedup vs baseline: 1.0082x; 1.0082x over previous
.LBB0_495:
	v_ashrrev_i32_e32 v8, 5, v3
	v_and_b32_e32 v9, 0x7c, v2
	v_lshlrev_b32_e32 v4, 9, v8
	v_lshl_add_u32 v4, v9, 2, v4
	s_mov_b64 s[8:9], s[6:7]
	s_waitcnt lgkmcnt(0)
	global_load_dwordx4 v[182:185], v4, s[8:9]
	s_add_u32 s8, s8, 0x2000
	s_addc_u32 s9, s9, 0
	global_load_dwordx4 v[186:189], v4, s[8:9]
	s_add_u32 s8, s8, 0x2000
	s_addc_u32 s9, s9, 0
	global_load_dwordx4 v[190:193], v4, s[8:9]
	s_add_u32 s8, s8, 0x2000
	s_addc_u32 s9, s9, 0
	global_load_dwordx4 v[194:197], v4, s[8:9]
	s_add_u32 s8, s8, 0x2000
	s_addc_u32 s9, s9, 0
	global_load_dwordx4 v[198:201], v4, s[8:9]
	s_add_u32 s8, s8, 0x2000
	s_addc_u32 s9, s9, 0
	global_load_dwordx4 v[202:205], v4, s[8:9]
	s_add_u32 s8, s8, 0x2000
	s_addc_u32 s9, s9, 0
	global_load_dwordx4 v[206:209], v4, s[8:9]
	s_add_u32 s8, s8, 0x2000
	s_addc_u32 s9, s9, 0
	global_load_dwordx4 v[210:213], v4, s[8:9]
	v_mul_lo_u32 v0, v8, s11
	v_lshlrev_b32_e32 v6, 1, v9
	v_add3_u32 v0, 0, v0, v6
	v_or_b32_e32 v6, 2, v9
	v_or_b32_e32 v7, 3, v9
	s_waitcnt vmcnt(0)
	v_cmp_le_i32_e32 vcc, v9, v8
	s_nop 1
	v_cndmask_b32_e32 v2, 0, v182, vcc
	v_cmp_lt_i32_e32 vcc, v9, v8
	s_nop 1
	v_cndmask_b32_e32 v3, 0, v183, vcc
	v_cvt_pk_bf16_f32 v4, v2, v3
	v_cmp_le_i32_e32 vcc, v6, v8
	s_nop 1
	v_cndmask_b32_e32 v2, 0, v184, vcc
	v_cmp_le_i32_e32 vcc, v7, v8
	s_nop 1
	v_cndmask_b32_e32 v3, 0, v185, vcc
	v_cvt_pk_bf16_f32 v5, v2, v3
	s_nop 0
	ds_write_b64 v0, v[4:5] offset:34816
	v_add_u32_e32 v8, 16, v8
	v_cmp_le_i32_e32 vcc, v9, v8
	s_nop 1
	v_cndmask_b32_e32 v2, 0, v186, vcc
	v_cmp_lt_i32_e32 vcc, v9, v8
	s_nop 1
	v_cndmask_b32_e32 v3, 0, v187, vcc
	v_cvt_pk_bf16_f32 v4, v2, v3
	v_cmp_le_i32_e32 vcc, v6, v8
	s_nop 1
	v_cndmask_b32_e32 v2, 0, v188, vcc
	v_cmp_le_i32_e32 vcc, v7, v8
	s_nop 1
	v_cndmask_b32_e32 v3, 0, v189, vcc
	v_cvt_pk_bf16_f32 v5, v2, v3
	s_nop 0
	ds_write_b64 v0, v[4:5] offset:39168
	v_add_u32_e32 v8, 16, v8
	v_cmp_le_i32_e32 vcc, v9, v8
	s_nop 1
	v_cndmask_b32_e32 v2, 0, v190, vcc
	v_cmp_lt_i32_e32 vcc, v9, v8
	s_nop 1
	v_cndmask_b32_e32 v3, 0, v191, vcc
	v_cvt_pk_bf16_f32 v4, v2, v3
	v_cmp_le_i32_e32 vcc, v6, v8
	s_nop 1
	v_cndmask_b32_e32 v2, 0, v192, vcc
	v_cmp_le_i32_e32 vcc, v7, v8
	s_nop 1
	v_cndmask_b32_e32 v3, 0, v193, vcc
	v_cvt_pk_bf16_f32 v5, v2, v3
	s_nop 0
	ds_write_b64 v0, v[4:5] offset:43520
	v_add_u32_e32 v8, 16, v8
	v_cmp_le_i32_e32 vcc, v9, v8
	s_nop 1
	v_cndmask_b32_e32 v2, 0, v194, vcc
	v_cmp_lt_i32_e32 vcc, v9, v8
	s_nop 1
	v_cndmask_b32_e32 v3, 0, v195, vcc
	v_cvt_pk_bf16_f32 v4, v2, v3
	v_cmp_le_i32_e32 vcc, v6, v8
	s_nop 1
	v_cndmask_b32_e32 v2, 0, v196, vcc
	v_cmp_le_i32_e32 vcc, v7, v8
	s_nop 1
	v_cndmask_b32_e32 v3, 0, v197, vcc
	v_cvt_pk_bf16_f32 v5, v2, v3
	s_nop 0
	ds_write_b64 v0, v[4:5] offset:47872
	v_add_u32_e32 v8, 16, v8
	v_cmp_le_i32_e32 vcc, v9, v8
	s_nop 1
	v_cndmask_b32_e32 v2, 0, v198, vcc
	v_cmp_lt_i32_e32 vcc, v9, v8
	s_nop 1
	v_cndmask_b32_e32 v3, 0, v199, vcc
	v_cvt_pk_bf16_f32 v4, v2, v3
	v_cmp_le_i32_e32 vcc, v6, v8
	s_nop 1
	v_cndmask_b32_e32 v2, 0, v200, vcc
	v_cmp_le_i32_e32 vcc, v7, v8
	s_nop 1
	v_cndmask_b32_e32 v3, 0, v201, vcc
	v_cvt_pk_bf16_f32 v5, v2, v3
	s_nop 0
	ds_write_b64 v0, v[4:5] offset:52224
	v_add_u32_e32 v8, 16, v8
	v_cmp_le_i32_e32 vcc, v9, v8
	s_nop 1
	v_cndmask_b32_e32 v2, 0, v202, vcc
	v_cmp_lt_i32_e32 vcc, v9, v8
	s_nop 1
	v_cndmask_b32_e32 v3, 0, v203, vcc
	v_cvt_pk_bf16_f32 v4, v2, v3
	v_cmp_le_i32_e32 vcc, v6, v8
	s_nop 1
	v_cndmask_b32_e32 v2, 0, v204, vcc
	v_cmp_le_i32_e32 vcc, v7, v8
	s_nop 1
	v_cndmask_b32_e32 v3, 0, v205, vcc
	v_cvt_pk_bf16_f32 v5, v2, v3
	s_nop 0
	ds_write_b64 v0, v[4:5] offset:56576
	v_add_u32_e32 v8, 16, v8
	v_cmp_le_i32_e32 vcc, v9, v8
	s_nop 1
	v_cndmask_b32_e32 v2, 0, v206, vcc
	v_cmp_lt_i32_e32 vcc, v9, v8
	s_nop 1
	v_cndmask_b32_e32 v3, 0, v207, vcc
	v_cvt_pk_bf16_f32 v4, v2, v3
	v_cmp_le_i32_e32 vcc, v6, v8
	s_nop 1
	v_cndmask_b32_e32 v2, 0, v208, vcc
	v_cmp_le_i32_e32 vcc, v7, v8
	s_nop 1
	v_cndmask_b32_e32 v3, 0, v209, vcc
	v_cvt_pk_bf16_f32 v5, v2, v3
	s_nop 0
	ds_write_b64 v0, v[4:5] offset:60928
	v_add_u32_e32 v8, 16, v8
	v_cmp_le_i32_e32 vcc, v9, v8
	s_nop 1
	v_cndmask_b32_e32 v2, 0, v210, vcc
	v_cmp_lt_i32_e32 vcc, v9, v8
	s_nop 1
	v_cndmask_b32_e32 v3, 0, v211, vcc
	v_cvt_pk_bf16_f32 v4, v2, v3
	v_cmp_le_i32_e32 vcc, v6, v8
	s_nop 1
	v_cndmask_b32_e32 v2, 0, v212, vcc
	v_cmp_le_i32_e32 vcc, v7, v8
	s_nop 1
	v_cndmask_b32_e32 v3, 0, v213, vcc
	v_cvt_pk_bf16_f32 v5, v2, v3
	s_nop 0
	ds_write_b64 v0, v[4:5] offset:65280

.LBB0_498:
	v_ashrrev_i32_e32 v11, 4, v10
	v_and_b32_e32 v20, -8, v11
	v_ashrrev_i32_e32 v21, 31, v20
	v_lshl_add_u64 v[2:3], v[20:21], 1, v[6:7]
	v_lshlrev_b64 v[16:17], 2, v[20:21]
	v_lshl_add_u64 v[22:23], s[6:7], 0, v[16:17]
	v_lshl_add_u64 v[24:25], s[8:9], 0, v[16:17]
	global_load_dwordx4 v[146:149], v[2:3], off
	global_load_dwordx4 v[150:153], v[2:3], off offset:64
	global_load_dwordx4 v[154:157], v[2:3], off offset:128
	global_load_dwordx4 v[158:161], v[2:3], off offset:192
	global_load_dwordx4 v[182:185], v[22:23], off
	global_load_dwordx4 v[186:189], v[22:23], off offset:16
	global_load_dwordx4 v[228:231], v[24:25], off
	global_load_dwordx4 v[232:235], v[24:25], off offset:16
	global_load_dwordx4 v[190:193], v[22:23], off offset:128
	global_load_dwordx4 v[194:197], v[22:23], off offset:144
	global_load_dwordx4 v[236:239], v[24:25], off offset:128
	global_load_dwordx4 v[240:243], v[24:25], off offset:144
	global_load_dwordx4 v[198:201], v[22:23], off offset:256
	global_load_dwordx4 v[202:205], v[22:23], off offset:272
	global_load_dwordx4 v[244:247], v[24:25], off offset:256
	global_load_dwordx4 v[248:251], v[24:25], off offset:272
	global_load_dwordx4 v[206:209], v[22:23], off offset:384
	global_load_dwordx4 v[210:213], v[22:23], off offset:400
	global_load_dwordx4 v[162:165], v[24:25], off offset:384
	global_load_dwordx4 v[124:127], v[24:25], off offset:400
	v_mad_u64_u32 v[20:21], s[14:15], v20, s13, v[0:1]
	s_waitcnt vmcnt(0) lgkmcnt(0)
	v_lshlrev_b32_e32 v12, 16, v146
	v_sub_f32_e32 v12, v12, v8
	v_mul_f32_e32 v12, v9, v12
	v_fma_f32 v12, v12, v182, v228
	v_cvt_pk_bf16_f32 v12, v12, v1
	s_nop 0
	ds_write_b16 v20, v12
	v_and_b32_e32 v13, 0xffff0000, v146
	v_sub_f32_e32 v13, v13, v8
	v_mul_f32_e32 v13, v9, v13
	v_fma_f32 v13, v13, v183, v229
	v_cvt_pk_bf16_f32 v13, v13, v1
	s_nop 0
	ds_write_b16 v20, v13 offset:272
	v_lshlrev_b32_e32 v14, 16, v147
	v_sub_f32_e32 v14, v14, v8
	v_mul_f32_e32 v14, v9, v14
	v_fma_f32 v14, v14, v184, v230
	v_cvt_pk_bf16_f32 v14, v14, v1
	s_nop 0
	ds_write_b16 v20, v14 offset:544
	v_and_b32_e32 v15, 0xffff0000, v147
	v_sub_f32_e32 v15, v15, v8
	v_mul_f32_e32 v15, v9, v15
	v_fma_f32 v15, v15, v185, v231
	v_cvt_pk_bf16_f32 v15, v15, v1
	s_nop 0
	ds_write_b16 v20, v15 offset:816
	v_lshlrev_b32_e32 v12, 16, v148
	v_sub_f32_e32 v12, v12, v8
	v_mul_f32_e32 v12, v9, v12
	v_fma_f32 v12, v12, v186, v232
	v_cvt_pk_bf16_f32 v12, v12, v1
	s_nop 0
	ds_write_b16 v20, v12 offset:1088
	v_and_b32_e32 v13, 0xffff0000, v148
	v_sub_f32_e32 v13, v13, v8
	v_mul_f32_e32 v13, v9, v13
	v_fma_f32 v13, v13, v187, v233
	v_cvt_pk_bf16_f32 v13, v13, v1
	s_nop 0
	ds_write_b16 v20, v13 offset:1360
	v_lshlrev_b32_e32 v14, 16, v149
	v_sub_f32_e32 v14, v14, v8
	v_mul_f32_e32 v14, v9, v14
	v_fma_f32 v14, v14, v188, v234
	v_cvt_pk_bf16_f32 v14, v14, v1
	s_nop 0
	ds_write_b16 v20, v14 offset:1632
	v_and_b32_e32 v15, 0xffff0000, v149
	v_sub_f32_e32 v15, v15, v8
	v_mul_f32_e32 v15, v9, v15
	v_fma_f32 v15, v15, v189, v235
	v_cvt_pk_bf16_f32 v15, v15, v1
	s_nop 0
	ds_write_b16 v20, v15 offset:1904
	v_lshlrev_b32_e32 v12, 16, v150
	v_sub_f32_e32 v12, v12, v8
	v_mul_f32_e32 v12, v9, v12
	v_fma_f32 v12, v12, v190, v236
	v_cvt_pk_bf16_f32 v12, v12, v1
	s_nop 0
	ds_write_b16 v20, v12 offset:8704
	v_and_b32_e32 v13, 0xffff0000, v150
	v_sub_f32_e32 v13, v13, v8
	v_mul_f32_e32 v13, v9, v13
	v_fma_f32 v13, v13, v191, v237
	v_cvt_pk_bf16_f32 v13, v13, v1
	s_nop 0
	ds_write_b16 v20, v13 offset:8976
	v_lshlrev_b32_e32 v14, 16, v151
	v_sub_f32_e32 v14, v14, v8
	v_mul_f32_e32 v14, v9, v14
	v_fma_f32 v14, v14, v192, v238
	v_cvt_pk_bf16_f32 v14, v14, v1
	s_nop 0
	ds_write_b16 v20, v14 offset:9248
	v_and_b32_e32 v15, 0xffff0000, v151
	v_sub_f32_e32 v15, v15, v8
	v_mul_f32_e32 v15, v9, v15
	v_fma_f32 v15, v15, v193, v239
	v_cvt_pk_bf16_f32 v15, v15, v1
	s_nop 0
	ds_write_b16 v20, v15 offset:9520
	v_lshlrev_b32_e32 v12, 16, v152
	v_sub_f32_e32 v12, v12, v8
	v_mul_f32_e32 v12, v9, v12
	v_fma_f32 v12, v12, v194, v240
	v_cvt_pk_bf16_f32 v12, v12, v1
	s_nop 0
	ds_write_b16 v20, v12 offset:9792
	v_and_b32_e32 v13, 0xffff0000, v152
	v_sub_f32_e32 v13, v13, v8
	v_mul_f32_e32 v13, v9, v13
	v_fma_f32 v13, v13, v195, v241
	v_cvt_pk_bf16_f32 v13, v13, v1
	s_nop 0
	ds_write_b16 v20, v13 offset:10064
	v_lshlrev_b32_e32 v14, 16, v153
	v_sub_f32_e32 v14, v14, v8
	v_mul_f32_e32 v14, v9, v14
	v_fma_f32 v14, v14, v196, v242
	v_cvt_pk_bf16_f32 v14, v14, v1
	s_nop 0
	ds_write_b16 v20, v14 offset:10336
	v_and_b32_e32 v15, 0xffff0000, v153
	v_sub_f32_e32 v15, v15, v8
	v_mul_f32_e32 v15, v9, v15
	v_fma_f32 v15, v15, v197, v243
	v_cvt_pk_bf16_f32 v15, v15, v1
	s_nop 0
	ds_write_b16 v20, v15 offset:10608
	v_lshlrev_b32_e32 v12, 16, v154
	v_sub_f32_e32 v12, v12, v8
	v_mul_f32_e32 v12, v9, v12
	v_fma_f32 v12, v12, v198, v244
	v_cvt_pk_bf16_f32 v12, v12, v1
	s_nop 0
	ds_write_b16 v20, v12 offset:17408
	v_and_b32_e32 v13, 0xffff0000, v154
	v_sub_f32_e32 v13, v13, v8
	v_mul_f32_e32 v13, v9, v13
	v_fma_f32 v13, v13, v199, v245
	v_cvt_pk_bf16_f32 v13, v13, v1
	s_nop 0
	ds_write_b16 v20, v13 offset:17680
	v_lshlrev_b32_e32 v14, 16, v155
	v_sub_f32_e32 v14, v14, v8
	v_mul_f32_e32 v14, v9, v14
	v_fma_f32 v14, v14, v200, v246
	v_cvt_pk_bf16_f32 v14, v14, v1
	s_nop 0
	ds_write_b16 v20, v14 offset:17952
	v_and_b32_e32 v15, 0xffff0000, v155
	v_sub_f32_e32 v15, v15, v8
	v_mul_f32_e32 v15, v9, v15
	v_fma_f32 v15, v15, v201, v247
	v_cvt_pk_bf16_f32 v15, v15, v1
	s_nop 0
	ds_write_b16 v20, v15 offset:18224
	v_lshlrev_b32_e32 v12, 16, v156
	v_sub_f32_e32 v12, v12, v8
	v_mul_f32_e32 v12, v9, v12
	v_fma_f32 v12, v12, v202, v248
	v_cvt_pk_bf16_f32 v12, v12, v1
	s_nop 0
	ds_write_b16 v20, v12 offset:18496
	v_and_b32_e32 v13, 0xffff0000, v156
	v_sub_f32_e32 v13, v13, v8
	v_mul_f32_e32 v13, v9, v13
	v_fma_f32 v13, v13, v203, v249
	v_cvt_pk_bf16_f32 v13, v13, v1
	s_nop 0
	ds_write_b16 v20, v13 offset:18768
	v_lshlrev_b32_e32 v14, 16, v157
	v_sub_f32_e32 v14, v14, v8
	v_mul_f32_e32 v14, v9, v14
	v_fma_f32 v14, v14, v204, v250
	v_cvt_pk_bf16_f32 v14, v14, v1
	s_nop 0
	ds_write_b16 v20, v14 offset:19040
	v_and_b32_e32 v15, 0xffff0000, v157
	v_sub_f32_e32 v15, v15, v8
	v_mul_f32_e32 v15, v9, v15
	v_fma_f32 v15, v15, v205, v251
	v_cvt_pk_bf16_f32 v15, v15, v1
	s_nop 0
	ds_write_b16 v20, v15 offset:19312
	v_lshlrev_b32_e32 v12, 16, v158
	v_sub_f32_e32 v12, v12, v8
	v_mul_f32_e32 v12, v9, v12
	v_fma_f32 v12, v12, v206, v162
	v_cvt_pk_bf16_f32 v12, v12, v1
	s_nop 0
	ds_write_b16 v20, v12 offset:26112
	v_and_b32_e32 v13, 0xffff0000, v158
	v_sub_f32_e32 v13, v13, v8
	v_mul_f32_e32 v13, v9, v13
	v_fma_f32 v13, v13, v207, v163
	v_cvt_pk_bf16_f32 v13, v13, v1
	s_nop 0
	ds_write_b16 v20, v13 offset:26384
	v_lshlrev_b32_e32 v14, 16, v159
	v_sub_f32_e32 v14, v14, v8
	v_mul_f32_e32 v14, v9, v14
	v_fma_f32 v14, v14, v208, v164
	v_cvt_pk_bf16_f32 v14, v14, v1
	s_nop 0
	ds_write_b16 v20, v14 offset:26656
	v_and_b32_e32 v15, 0xffff0000, v159
	v_sub_f32_e32 v15, v15, v8
	v_mul_f32_e32 v15, v9, v15
	v_fma_f32 v15, v15, v209, v165
	v_cvt_pk_bf16_f32 v15, v15, v1
	s_nop 0
	ds_write_b16 v20, v15 offset:26928
	v_lshlrev_b32_e32 v12, 16, v160
	v_sub_f32_e32 v12, v12, v8
	v_mul_f32_e32 v12, v9, v12
	v_fma_f32 v12, v12, v210, v124
	v_cvt_pk_bf16_f32 v12, v12, v1
	s_nop 0
	ds_write_b16 v20, v12 offset:27200
	v_and_b32_e32 v13, 0xffff0000, v160
	v_sub_f32_e32 v13, v13, v8
	v_mul_f32_e32 v13, v9, v13
	v_fma_f32 v13, v13, v211, v125
	v_cvt_pk_bf16_f32 v13, v13, v1
	s_nop 0
	ds_write_b16 v20, v13 offset:27472
	v_lshlrev_b32_e32 v14, 16, v161
	v_sub_f32_e32 v14, v14, v8
	v_mul_f32_e32 v14, v9, v14
	v_fma_f32 v14, v14, v212, v126
	v_cvt_pk_bf16_f32 v14, v14, v1
	s_nop 0
	ds_write_b16 v20, v14 offset:27744
	v_and_b32_e32 v15, 0xffff0000, v161
	v_sub_f32_e32 v15, v15, v8
	v_mul_f32_e32 v15, v9, v15
	v_fma_f32 v15, v15, v213, v127
	v_cvt_pk_bf16_f32 v15, v15, v1
	s_nop 0
	ds_write_b16 v20, v15 offset:28016

.LBB0_967:
	v_add_u32_e32 v7, 0x200, v6
	v_ashrrev_i32_e32 v15, 6, v7
	v_add_u32_e32 v7, 0x400, v6
	v_ashrrev_i32_e32 v16, 6, v7
	v_add_u32_e32 v7, 0x600, v6
	v_ashrrev_i32_e32 v17, 6, v7
	v_add_u32_e32 v7, 0x800, v6
	v_ashrrev_i32_e32 v18, 6, v7
	v_add_u32_e32 v7, 0xa00, v6
	v_ashrrev_i32_e32 v13, 3, v6
	v_lshlrev_b32_e32 v0, 3, v6
	v_ashrrev_i32_e32 v14, 6, v6
	v_ashrrev_i32_e32 v19, 6, v7
	v_add_u32_e32 v7, 0xc00, v6
	v_add_u32_e32 v6, 0xe00, v6
	v_and_b32_e32 v0, 56, v0
	v_ashrrev_i32_e32 v20, 6, v7
	v_ashrrev_i32_e32 v23, 6, v6
	s_movk_i32 s7, 0x104
	v_lshl_add_u32 v4, v2, 2, 0
	v_lshl_add_u32 v5, v13, 2, 0
	v_mul_lo_u32 v6, v14, s7
	v_mul_lo_u32 v7, v15, s7
	v_mul_lo_u32 v26, v16, s7
	v_mul_lo_u32 v27, v17, s7
	v_mul_lo_u32 v28, v18, s7
	v_mul_lo_u32 v29, v19, s7
	v_mul_lo_u32 v30, v20, s7
	v_mul_u32_u24_e32 v32, 0x104, v0
	v_mul_lo_u32 v31, v23, s7
	v_add_u32_e32 v24, v4, v6
	v_add_u32_e32 v25, v4, v7
	v_add_u32_e32 v26, v4, v26
	v_add_u32_e32 v27, v4, v27
	v_add_u32_e32 v28, v4, v28
	v_add_u32_e32 v29, v4, v29
	v_add_u32_e32 v30, v4, v30
	v_add_u32_e32 v31, v4, v31
	v_add_u32_e32 v32, v5, v32
	v_lshlrev_b32_e32 v4, 1, v0
	s_mov_b32 s9, s69
	s_waitcnt vmcnt(0)
	v_mov_b32_e32 v33, v3
	v_mov_b32_e32 v0, v8
	v_mov_b32_e32 v35, v10
	v_mov_b32_e32 v34, v9
	v_mov_b32_e32 v37, v12
	v_mov_b32_e32 v36, v11
	v_mov_b32_e32 v39, v22
	v_mov_b32_e32 v38, v21
	s_branch .LBB0_969
.LBB0_968:
	s_or_b64 exec, exec, s[20:21]
	ds_write_b32 v24, v3
	ds_write_b32 v25, v8
	ds_write_b32 v26, v10
	ds_write_b32 v27, v9
	ds_write_b32 v28, v12
	ds_write_b32 v29, v11
	ds_write_b32 v30, v22
	ds_write_b32 v31, v21
	s_waitcnt lgkmcnt(0)
	s_barrier
	ds_read2_b32 v[6:7], v32 offset1:65
	ds_read2_b32 v[8:9], v32 offset0:130 offset1:195
	v_add_u32_e32 v3, 0x400, v32
	ds_read2_b32 v[10:11], v3 offset0:4 offset1:69
	ds_read2_b32 v[40:41], v3 offset0:134 offset1:199
	v_add_u32_e32 v3, s8, v13
	v_ashrrev_i32_e32 v5, 31, v3
	s_waitcnt lgkmcnt(3)
	v_cvt_pk_bf16_f32 v6, v6, v7
	s_waitcnt lgkmcnt(2)
	v_cvt_pk_bf16_f32 v7, v8, v9
	s_waitcnt lgkmcnt(1)
	v_cvt_pk_bf16_f32 v8, v10, v11
	v_mul_lo_u32 v5, s4, v5
	v_mul_lo_u32 v12, s5, v3
	v_mad_u64_u32 v[10:11], s[4:5], s4, v3, 0
	v_add3_u32 v11, v11, v5, v12
	v_lshl_add_u64 v[10:11], v[10:11], 1, s[0:1]
	s_ashr_i32 s7, s6, 31
	v_lshl_add_u64 v[10:11], s[6:7], 1, v[10:11]
	v_mov_b32_e32 v5, v1
	s_waitcnt lgkmcnt(0)
	v_cvt_pk_bf16_f32 v9, v40, v41
	v_lshl_add_u64 v[10:11], v[10:11], 0, v[4:5]
	global_store_dwordx4 v[10:11], v[6:9], off
	s_andn2_b64 vcc, exec, s[10:11]
	s_mov_b32 s8, s14
	s_mov_b32 s6, s37
	s_mov_b64 s[4:5], s[16:17]
	s_mov_b64 s[0:1], s[12:13]
	s_waitcnt lgkmcnt(0)
	s_barrier
	s_cbranch_vccz .LBB0_1005

.LBB0_988:
	s_waitcnt vmcnt(1)
	v_mov_b32_e32 v3, v33
	v_mov_b32_e32 v8, v0
	v_mov_b32_e32 v10, v35
	v_mov_b32_e32 v9, v34
	v_mov_b32_e32 v12, v37
	v_mov_b32_e32 v11, v36
	v_mov_b32_e32 v22, v39
	v_mov_b32_e32 v21, v38
	v_add_u32_e32 v0, s14, v2
	v_cmp_gt_i32_e32 vcc, s7, v0
	s_ashr_i32 s15, s14, 31
	s_and_b64 s[18:19], s[18:19], vcc
	s_lshl_b64 s[20:21], s[14:15], 2
	s_add_u32 s20, s22, s20
	s_addc_u32 s21, s23, s21
	v_lshlrev_b32_e32 v0, 2, v2
	v_lshl_add_u64 v[6:7], s[20:21], 0, v[0:1]
	v_mov_b32_e32 v0, 0
	v_mov_b32_e32 v33, 0
	s_and_saveexec_b64 s[20:21], s[18:19]
	s_cbranch_execz .LBB0_990
	v_add_u32_e32 v5, s37, v14
	v_mad_u64_u32 v[34:35], s[22:23], v5, s7, 0
	v_ashrrev_i32_e32 v33, 31, v5
	v_mov_b32_e32 v36, v35
	v_mad_u64_u32 v[36:37], s[22:23], v33, s7, v[36:37]
	v_mov_b32_e32 v35, v36
	v_lshl_add_u64 v[34:35], v[34:35], 2, v[6:7]
	global_load_dword v33, v[34:35], off
